# v7: all ten GEMM epilogue kinds hand-written (PROJN scale/silu tiles added); compiler epilogue no longer reached
# speedup vs baseline: 1.0474x; 1.0110x over previous
.LBB0_435:
	s_cmp_eq_u32 s31, 2
	s_cbranch_scc1 .Lepi_ya
	s_cmp_eq_u32 s31, 6
	s_cbranch_scc1 .Lepi_yb
	s_cmp_eq_u32 s31, 7
	s_cbranch_scc1 .Lepi_wout
	s_cmp_eq_u32 s31, 9
	s_cbranch_scc1 .Lepi_w2
	s_cmp_eq_u32 s31, 3
	s_cbranch_scc1 .Lepi_qup
	s_cmp_eq_u32 s31, 4
	s_cbranch_scc1 .Lepi_kup
	s_cmp_eq_u32 s31, 5
	s_cbranch_scc1 .Lepi_vupt
	s_cmp_lg_u32 s31, 0
	s_cbranch_scc1 .Lepi_noprojn
	s_add_i32 s46, s8, -6
	s_cmp_lt_u32 s46, 8
	s_cbranch_scc1 .Lepi_projn_g
	s_cmp_lt_u32 s8, 2
	s_cbranch_scc1 .Lepi_projn_sc
	s_cmp_lt_u32 s8, 6
	s_cbranch_scc1 .Lepi_projn_silu
	s_cmp_ge_u32 s8, 14
	s_cbranch_scc1 .Lepi_projn_lat

.Lepi_projn_sc:
	s_lshl_b32 s9, s9, 8
	s_add_i32 s9, s9, s60
	s_lshl_b32 s78, s8, 8
	s_or_b32 s78, s78, s26
	s_mov_b32 s8, s9
	s_mul_i32 s9, s9, 0x400
	s_mul_i32 s41, s78, 2
	s_add_i32 s9, s9, s41
	s_add_u32 s46, s36, s9
	s_addc_u32 s47, s37, 0
	s_add_u32 s46, s46, 0x17600000
	s_addc_u32 s47, s47, 0
	v_lshlrev_b32_e32 v130, 10, v1
	v_lshl_add_u32 v130, v176, 1, v130
	s_mov_b32 s8, 0x3db504f3
	v_mul_f32_e32 v152, s8, v126
	v_mul_f32_e32 v153, s8, v127
	v_mul_f32_e32 v154, s8, v128
	v_mul_f32_e32 v155, s8, v129
	v_mul_f32_e32 v156, s8, v122
	v_mul_f32_e32 v157, s8, v123
	v_mul_f32_e32 v158, s8, v124
	v_mul_f32_e32 v159, s8, v125
	v_cvt_pk_bf16_f32 v132, v152, v153
	v_cvt_pk_bf16_f32 v133, v154, v155
	v_cvt_pk_bf16_f32 v134, v156, v157
	v_cvt_pk_bf16_f32 v135, v158, v159
	global_store_dwordx4 v130, v[132:135], s[46:47]
	v_mul_f32_e32 v160, s8, v118
	v_mul_f32_e32 v161, s8, v119
	v_mul_f32_e32 v162, s8, v120
	v_mul_f32_e32 v163, s8, v121
	v_mul_f32_e32 v164, s8, v114
	v_mul_f32_e32 v165, s8, v115
	v_mul_f32_e32 v166, s8, v116
	v_mul_f32_e32 v167, s8, v117
	v_cvt_pk_bf16_f32 v168, v160, v161
	v_cvt_pk_bf16_f32 v169, v162, v163
	v_cvt_pk_bf16_f32 v170, v164, v165
	v_cvt_pk_bf16_f32 v171, v166, v167
	global_store_dwordx4 v130, v[168:171], s[46:47] offset:256
	v_mul_f32_e32 v152, s8, v110
	v_mul_f32_e32 v153, s8, v111
	v_mul_f32_e32 v154, s8, v112
	v_mul_f32_e32 v155, s8, v113
	v_mul_f32_e32 v156, s8, v106
	v_mul_f32_e32 v157, s8, v107
	v_mul_f32_e32 v158, s8, v108
	v_mul_f32_e32 v159, s8, v109
	v_cvt_pk_bf16_f32 v132, v152, v153
	v_cvt_pk_bf16_f32 v133, v154, v155
	v_cvt_pk_bf16_f32 v134, v156, v157
	v_cvt_pk_bf16_f32 v135, v158, v159
	s_add_u32 s46, s46, 0x4000
	s_addc_u32 s47, s47, 0
	global_store_dwordx4 v130, v[132:135], s[46:47]
	v_mul_f32_e32 v160, s8, v102
	v_mul_f32_e32 v161, s8, v103
	v_mul_f32_e32 v162, s8, v104
	v_mul_f32_e32 v163, s8, v105
	v_mul_f32_e32 v164, s8, v98
	v_mul_f32_e32 v165, s8, v99
	v_mul_f32_e32 v166, s8, v100
	v_mul_f32_e32 v167, s8, v101
	v_cvt_pk_bf16_f32 v168, v160, v161
	v_cvt_pk_bf16_f32 v169, v162, v163
	v_cvt_pk_bf16_f32 v170, v164, v165
	v_cvt_pk_bf16_f32 v171, v166, v167
	global_store_dwordx4 v130, v[168:171], s[46:47] offset:256
	v_mul_f32_e32 v152, s8, v94
	v_mul_f32_e32 v153, s8, v95
	v_mul_f32_e32 v154, s8, v96
	v_mul_f32_e32 v155, s8, v97
	v_mul_f32_e32 v156, s8, v90
	v_mul_f32_e32 v157, s8, v91
	v_mul_f32_e32 v158, s8, v92
	v_mul_f32_e32 v159, s8, v93
	v_cvt_pk_bf16_f32 v132, v152, v153
	v_cvt_pk_bf16_f32 v133, v154, v155
	v_cvt_pk_bf16_f32 v134, v156, v157
	v_cvt_pk_bf16_f32 v135, v158, v159
	s_add_u32 s46, s46, 0x4000
	s_addc_u32 s47, s47, 0
	global_store_dwordx4 v130, v[132:135], s[46:47]
	v_mul_f32_e32 v160, s8, v86
	v_mul_f32_e32 v161, s8, v87
	v_mul_f32_e32 v162, s8, v88
	v_mul_f32_e32 v163, s8, v89
	v_mul_f32_e32 v164, s8, v82
	v_mul_f32_e32 v165, s8, v83
	v_mul_f32_e32 v166, s8, v84
	v_mul_f32_e32 v167, s8, v85
	v_cvt_pk_bf16_f32 v168, v160, v161
	v_cvt_pk_bf16_f32 v169, v162, v163
	v_cvt_pk_bf16_f32 v170, v164, v165
	v_cvt_pk_bf16_f32 v171, v166, v167
	global_store_dwordx4 v130, v[168:171], s[46:47] offset:256
	v_mul_f32_e32 v152, s8, v78
	v_mul_f32_e32 v153, s8, v79
	v_mul_f32_e32 v154, s8, v80
	v_mul_f32_e32 v155, s8, v81
	v_mul_f32_e32 v156, s8, v74
	v_mul_f32_e32 v157, s8, v75
	v_mul_f32_e32 v158, s8, v76
	v_mul_f32_e32 v159, s8, v77
	v_cvt_pk_bf16_f32 v132, v152, v153
	v_cvt_pk_bf16_f32 v133, v154, v155
	v_cvt_pk_bf16_f32 v134, v156, v157
	v_cvt_pk_bf16_f32 v135, v158, v159
	s_add_u32 s46, s46, 0x4000
	s_addc_u32 s47, s47, 0
	global_store_dwordx4 v130, v[132:135], s[46:47]
	v_mul_f32_e32 v160, s8, v70
	v_mul_f32_e32 v161, s8, v71
	v_mul_f32_e32 v162, s8, v72
	v_mul_f32_e32 v163, s8, v73
	v_mul_f32_e32 v164, s8, v66
	v_mul_f32_e32 v165, s8, v67
	v_mul_f32_e32 v166, s8, v68
	v_mul_f32_e32 v167, s8, v69
	v_cvt_pk_bf16_f32 v168, v160, v161
	v_cvt_pk_bf16_f32 v169, v162, v163
	v_cvt_pk_bf16_f32 v170, v164, v165
	v_cvt_pk_bf16_f32 v171, v166, v167
	global_store_dwordx4 v130, v[168:171], s[46:47] offset:256
	v_mul_f32_e32 v152, s8, v62
	v_mul_f32_e32 v153, s8, v63
	v_mul_f32_e32 v154, s8, v64
	v_mul_f32_e32 v155, s8, v65
	v_mul_f32_e32 v156, s8, v58
	v_mul_f32_e32 v157, s8, v59
	v_mul_f32_e32 v158, s8, v60
	v_mul_f32_e32 v159, s8, v61
	v_cvt_pk_bf16_f32 v132, v152, v153
	v_cvt_pk_bf16_f32 v133, v154, v155
	v_cvt_pk_bf16_f32 v134, v156, v157
	v_cvt_pk_bf16_f32 v135, v158, v159
	s_add_u32 s46, s46, 0x14000
	s_addc_u32 s47, s47, 0
	global_store_dwordx4 v130, v[132:135], s[46:47]
	v_mul_f32_e32 v160, s8, v54
	v_mul_f32_e32 v161, s8, v55
	v_mul_f32_e32 v162, s8, v56
	v_mul_f32_e32 v163, s8, v57
	v_mul_f32_e32 v164, s8, v50
	v_mul_f32_e32 v165, s8, v51
	v_mul_f32_e32 v166, s8, v52
	v_mul_f32_e32 v167, s8, v53
	v_cvt_pk_bf16_f32 v168, v160, v161
	v_cvt_pk_bf16_f32 v169, v162, v163
	v_cvt_pk_bf16_f32 v170, v164, v165
	v_cvt_pk_bf16_f32 v171, v166, v167
	global_store_dwordx4 v130, v[168:171], s[46:47] offset:256
	v_mul_f32_e32 v152, s8, v46
	v_mul_f32_e32 v153, s8, v47
	v_mul_f32_e32 v154, s8, v48
	v_mul_f32_e32 v155, s8, v49
	v_mul_f32_e32 v156, s8, v42
	v_mul_f32_e32 v157, s8, v43
	v_mul_f32_e32 v158, s8, v44
	v_mul_f32_e32 v159, s8, v45
	v_cvt_pk_bf16_f32 v132, v152, v153
	v_cvt_pk_bf16_f32 v133, v154, v155
	v_cvt_pk_bf16_f32 v134, v156, v157
	v_cvt_pk_bf16_f32 v135, v158, v159
	s_add_u32 s46, s46, 0x4000
	s_addc_u32 s47, s47, 0
	global_store_dwordx4 v130, v[132:135], s[46:47]
	v_mul_f32_e32 v160, s8, v38
	v_mul_f32_e32 v161, s8, v39
	v_mul_f32_e32 v162, s8, v40
	v_mul_f32_e32 v163, s8, v41
	v_mul_f32_e32 v164, s8, v34
	v_mul_f32_e32 v165, s8, v35
	v_mul_f32_e32 v166, s8, v36
	v_mul_f32_e32 v167, s8, v37
	v_cvt_pk_bf16_f32 v168, v160, v161
	v_cvt_pk_bf16_f32 v169, v162, v163
	v_cvt_pk_bf16_f32 v170, v164, v165
	v_cvt_pk_bf16_f32 v171, v166, v167
	global_store_dwordx4 v130, v[168:171], s[46:47] offset:256
	v_mul_f32_e32 v152, s8, v30
	v_mul_f32_e32 v153, s8, v31
	v_mul_f32_e32 v154, s8, v32
	v_mul_f32_e32 v155, s8, v33
	v_mul_f32_e32 v156, s8, v26
	v_mul_f32_e32 v157, s8, v27
	v_mul_f32_e32 v158, s8, v28
	v_mul_f32_e32 v159, s8, v29
	v_cvt_pk_bf16_f32 v132, v152, v153
	v_cvt_pk_bf16_f32 v133, v154, v155
	v_cvt_pk_bf16_f32 v134, v156, v157
	v_cvt_pk_bf16_f32 v135, v158, v159
	s_add_u32 s46, s46, 0x4000
	s_addc_u32 s47, s47, 0
	global_store_dwordx4 v130, v[132:135], s[46:47]
	v_mul_f32_e32 v160, s8, v22
	v_mul_f32_e32 v161, s8, v23
	v_mul_f32_e32 v162, s8, v24
	v_mul_f32_e32 v163, s8, v25
	v_mul_f32_e32 v164, s8, v18
	v_mul_f32_e32 v165, s8, v19
	v_mul_f32_e32 v166, s8, v20
	v_mul_f32_e32 v167, s8, v21
	v_cvt_pk_bf16_f32 v168, v160, v161
	v_cvt_pk_bf16_f32 v169, v162, v163
	v_cvt_pk_bf16_f32 v170, v164, v165
	v_cvt_pk_bf16_f32 v171, v166, v167
	global_store_dwordx4 v130, v[168:171], s[46:47] offset:256
	v_mul_f32_e32 v152, s8, v14
	v_mul_f32_e32 v153, s8, v15
	v_mul_f32_e32 v154, s8, v16
	v_mul_f32_e32 v155, s8, v17
	v_mul_f32_e32 v156, s8, v10
	v_mul_f32_e32 v157, s8, v11
	v_mul_f32_e32 v158, s8, v12
	v_mul_f32_e32 v159, s8, v13
	v_cvt_pk_bf16_f32 v132, v152, v153
	v_cvt_pk_bf16_f32 v133, v154, v155
	v_cvt_pk_bf16_f32 v134, v156, v157
	v_cvt_pk_bf16_f32 v135, v158, v159
	s_add_u32 s46, s46, 0x4000
	s_addc_u32 s47, s47, 0
	global_store_dwordx4 v130, v[132:135], s[46:47]
	v_mul_f32_e32 v160, s8, v6
	v_mul_f32_e32 v161, s8, v7
	v_mul_f32_e32 v162, s8, v8
	v_mul_f32_e32 v163, s8, v9
	v_mul_f32_e32 v164, s8, v2
	v_mul_f32_e32 v165, s8, v3
	v_mul_f32_e32 v166, s8, v4
	v_mul_f32_e32 v167, s8, v5
	v_cvt_pk_bf16_f32 v168, v160, v161
	v_cvt_pk_bf16_f32 v169, v162, v163
	v_cvt_pk_bf16_f32 v170, v164, v165
	v_cvt_pk_bf16_f32 v171, v166, v167
	global_store_dwordx4 v130, v[168:171], s[46:47] offset:256
	s_branch .LBB0_1251
.Lepi_projn_silu:
	s_lshl_b32 s9, s9, 8
	s_add_i32 s9, s9, s60
	s_lshl_b32 s78, s8, 8
	s_or_b32 s78, s78, s26
	s_add_i32 s78, s78, 0xfffffe00
	s_lshl_b32 s9, s9, 11
	s_lshl_b32 s78, s78, 1
	s_add_i32 s9, s9, s78
	s_add_u32 s46, s36, s9
	s_addc_u32 s47, s37, 0
	s_add_u32 s46, s46, 0xb600000
	s_addc_u32 s47, s47, 0
	v_lshlrev_b32_e32 v130, 11, v1
	v_lshl_add_u32 v130, v176, 1, v130
	v_mul_f32_e32 v152, 0xbfb8aa3b, v126
	v_mul_f32_e32 v153, 0xbfb8aa3b, v127
	v_mul_f32_e32 v154, 0xbfb8aa3b, v128
	v_mul_f32_e32 v155, 0xbfb8aa3b, v129
	v_mul_f32_e32 v156, 0xbfb8aa3b, v122
	v_mul_f32_e32 v157, 0xbfb8aa3b, v123
	v_mul_f32_e32 v158, 0xbfb8aa3b, v124
	v_mul_f32_e32 v159, 0xbfb8aa3b, v125
	v_exp_f32_e32 v152, v152
	v_exp_f32_e32 v153, v153
	v_exp_f32_e32 v154, v154
	v_exp_f32_e32 v155, v155
	v_exp_f32_e32 v156, v156
	v_exp_f32_e32 v157, v157
	v_exp_f32_e32 v158, v158
	v_exp_f32_e32 v159, v159
	v_add_f32_e32 v152, 1.0, v152
	v_add_f32_e32 v153, 1.0, v153
	v_add_f32_e32 v154, 1.0, v154
	v_add_f32_e32 v155, 1.0, v155
	v_add_f32_e32 v156, 1.0, v156
	v_add_f32_e32 v157, 1.0, v157
	v_add_f32_e32 v158, 1.0, v158
	v_add_f32_e32 v159, 1.0, v159
	v_rcp_f32_e32 v152, v152
	v_rcp_f32_e32 v153, v153
	v_rcp_f32_e32 v154, v154
	v_rcp_f32_e32 v155, v155
	v_rcp_f32_e32 v156, v156
	v_rcp_f32_e32 v157, v157
	v_rcp_f32_e32 v158, v158
	v_rcp_f32_e32 v159, v159
	v_mul_f32_e32 v152, v126, v152
	v_mul_f32_e32 v153, v127, v153
	v_mul_f32_e32 v154, v128, v154
	v_mul_f32_e32 v155, v129, v155
	v_mul_f32_e32 v156, v122, v156
	v_mul_f32_e32 v157, v123, v157
	v_mul_f32_e32 v158, v124, v158
	v_mul_f32_e32 v159, v125, v159
	v_cvt_pk_bf16_f32 v132, v152, v153
	v_cvt_pk_bf16_f32 v133, v154, v155
	v_cvt_pk_bf16_f32 v134, v156, v157
	v_cvt_pk_bf16_f32 v135, v158, v159
	global_store_dwordx4 v130, v[132:135], s[46:47] nt
	v_mul_f32_e32 v160, 0xbfb8aa3b, v118
	v_mul_f32_e32 v161, 0xbfb8aa3b, v119
	v_mul_f32_e32 v162, 0xbfb8aa3b, v120
	v_mul_f32_e32 v163, 0xbfb8aa3b, v121
	v_mul_f32_e32 v164, 0xbfb8aa3b, v114
	v_mul_f32_e32 v165, 0xbfb8aa3b, v115
	v_mul_f32_e32 v166, 0xbfb8aa3b, v116
	v_mul_f32_e32 v167, 0xbfb8aa3b, v117
	v_exp_f32_e32 v160, v160
	v_exp_f32_e32 v161, v161
	v_exp_f32_e32 v162, v162
	v_exp_f32_e32 v163, v163
	v_exp_f32_e32 v164, v164
	v_exp_f32_e32 v165, v165
	v_exp_f32_e32 v166, v166
	v_exp_f32_e32 v167, v167
	v_add_f32_e32 v160, 1.0, v160
	v_add_f32_e32 v161, 1.0, v161
	v_add_f32_e32 v162, 1.0, v162
	v_add_f32_e32 v163, 1.0, v163
	v_add_f32_e32 v164, 1.0, v164
	v_add_f32_e32 v165, 1.0, v165
	v_add_f32_e32 v166, 1.0, v166
	v_add_f32_e32 v167, 1.0, v167
	v_rcp_f32_e32 v160, v160
	v_rcp_f32_e32 v161, v161
	v_rcp_f32_e32 v162, v162
	v_rcp_f32_e32 v163, v163
	v_rcp_f32_e32 v164, v164
	v_rcp_f32_e32 v165, v165
	v_rcp_f32_e32 v166, v166
	v_rcp_f32_e32 v167, v167
	v_mul_f32_e32 v160, v118, v160
	v_mul_f32_e32 v161, v119, v161
	v_mul_f32_e32 v162, v120, v162
	v_mul_f32_e32 v163, v121, v163
	v_mul_f32_e32 v164, v114, v164
	v_mul_f32_e32 v165, v115, v165
	v_mul_f32_e32 v166, v116, v166
	v_mul_f32_e32 v167, v117, v167
	v_cvt_pk_bf16_f32 v168, v160, v161
	v_cvt_pk_bf16_f32 v169, v162, v163
	v_cvt_pk_bf16_f32 v170, v164, v165
	v_cvt_pk_bf16_f32 v171, v166, v167
	global_store_dwordx4 v130, v[168:171], s[46:47] offset:256 nt
	v_mul_f32_e32 v152, 0xbfb8aa3b, v110
	v_mul_f32_e32 v153, 0xbfb8aa3b, v111
	v_mul_f32_e32 v154, 0xbfb8aa3b, v112
	v_mul_f32_e32 v155, 0xbfb8aa3b, v113
	v_mul_f32_e32 v156, 0xbfb8aa3b, v106
	v_mul_f32_e32 v157, 0xbfb8aa3b, v107
	v_mul_f32_e32 v158, 0xbfb8aa3b, v108
	v_mul_f32_e32 v159, 0xbfb8aa3b, v109
	v_exp_f32_e32 v152, v152
	v_exp_f32_e32 v153, v153
	v_exp_f32_e32 v154, v154
	v_exp_f32_e32 v155, v155
	v_exp_f32_e32 v156, v156
	v_exp_f32_e32 v157, v157
	v_exp_f32_e32 v158, v158
	v_exp_f32_e32 v159, v159
	v_add_f32_e32 v152, 1.0, v152
	v_add_f32_e32 v153, 1.0, v153
	v_add_f32_e32 v154, 1.0, v154
	v_add_f32_e32 v155, 1.0, v155
	v_add_f32_e32 v156, 1.0, v156
	v_add_f32_e32 v157, 1.0, v157
	v_add_f32_e32 v158, 1.0, v158
	v_add_f32_e32 v159, 1.0, v159
	v_rcp_f32_e32 v152, v152
	v_rcp_f32_e32 v153, v153
	v_rcp_f32_e32 v154, v154
	v_rcp_f32_e32 v155, v155
	v_rcp_f32_e32 v156, v156
	v_rcp_f32_e32 v157, v157
	v_rcp_f32_e32 v158, v158
	v_rcp_f32_e32 v159, v159
	v_mul_f32_e32 v152, v110, v152
	v_mul_f32_e32 v153, v111, v153
	v_mul_f32_e32 v154, v112, v154
	v_mul_f32_e32 v155, v113, v155
	v_mul_f32_e32 v156, v106, v156
	v_mul_f32_e32 v157, v107, v157
	v_mul_f32_e32 v158, v108, v158
	v_mul_f32_e32 v159, v109, v159
	v_cvt_pk_bf16_f32 v132, v152, v153
	v_cvt_pk_bf16_f32 v133, v154, v155
	v_cvt_pk_bf16_f32 v134, v156, v157
	v_cvt_pk_bf16_f32 v135, v158, v159
	s_add_u32 s46, s46, 0x8000
	s_addc_u32 s47, s47, 0
	global_store_dwordx4 v130, v[132:135], s[46:47] nt
	v_mul_f32_e32 v160, 0xbfb8aa3b, v102
	v_mul_f32_e32 v161, 0xbfb8aa3b, v103
	v_mul_f32_e32 v162, 0xbfb8aa3b, v104
	v_mul_f32_e32 v163, 0xbfb8aa3b, v105
	v_mul_f32_e32 v164, 0xbfb8aa3b, v98
	v_mul_f32_e32 v165, 0xbfb8aa3b, v99
	v_mul_f32_e32 v166, 0xbfb8aa3b, v100
	v_mul_f32_e32 v167, 0xbfb8aa3b, v101
	v_exp_f32_e32 v160, v160
	v_exp_f32_e32 v161, v161
	v_exp_f32_e32 v162, v162
	v_exp_f32_e32 v163, v163
	v_exp_f32_e32 v164, v164
	v_exp_f32_e32 v165, v165
	v_exp_f32_e32 v166, v166
	v_exp_f32_e32 v167, v167
	v_add_f32_e32 v160, 1.0, v160
	v_add_f32_e32 v161, 1.0, v161
	v_add_f32_e32 v162, 1.0, v162
	v_add_f32_e32 v163, 1.0, v163
	v_add_f32_e32 v164, 1.0, v164
	v_add_f32_e32 v165, 1.0, v165
	v_add_f32_e32 v166, 1.0, v166
	v_add_f32_e32 v167, 1.0, v167
	v_rcp_f32_e32 v160, v160
	v_rcp_f32_e32 v161, v161
	v_rcp_f32_e32 v162, v162
	v_rcp_f32_e32 v163, v163
	v_rcp_f32_e32 v164, v164
	v_rcp_f32_e32 v165, v165
	v_rcp_f32_e32 v166, v166
	v_rcp_f32_e32 v167, v167
	v_mul_f32_e32 v160, v102, v160
	v_mul_f32_e32 v161, v103, v161
	v_mul_f32_e32 v162, v104, v162
	v_mul_f32_e32 v163, v105, v163
	v_mul_f32_e32 v164, v98, v164
	v_mul_f32_e32 v165, v99, v165
	v_mul_f32_e32 v166, v100, v166
	v_mul_f32_e32 v167, v101, v167
	v_cvt_pk_bf16_f32 v168, v160, v161
	v_cvt_pk_bf16_f32 v169, v162, v163
	v_cvt_pk_bf16_f32 v170, v164, v165
	v_cvt_pk_bf16_f32 v171, v166, v167
	global_store_dwordx4 v130, v[168:171], s[46:47] offset:256 nt
	v_mul_f32_e32 v152, 0xbfb8aa3b, v94
	v_mul_f32_e32 v153, 0xbfb8aa3b, v95
	v_mul_f32_e32 v154, 0xbfb8aa3b, v96
	v_mul_f32_e32 v155, 0xbfb8aa3b, v97
	v_mul_f32_e32 v156, 0xbfb8aa3b, v90
	v_mul_f32_e32 v157, 0xbfb8aa3b, v91
	v_mul_f32_e32 v158, 0xbfb8aa3b, v92
	v_mul_f32_e32 v159, 0xbfb8aa3b, v93
	v_exp_f32_e32 v152, v152
	v_exp_f32_e32 v153, v153
	v_exp_f32_e32 v154, v154
	v_exp_f32_e32 v155, v155
	v_exp_f32_e32 v156, v156
	v_exp_f32_e32 v157, v157
	v_exp_f32_e32 v158, v158
	v_exp_f32_e32 v159, v159
	v_add_f32_e32 v152, 1.0, v152
	v_add_f32_e32 v153, 1.0, v153
	v_add_f32_e32 v154, 1.0, v154
	v_add_f32_e32 v155, 1.0, v155
	v_add_f32_e32 v156, 1.0, v156
	v_add_f32_e32 v157, 1.0, v157
	v_add_f32_e32 v158, 1.0, v158
	v_add_f32_e32 v159, 1.0, v159
	v_rcp_f32_e32 v152, v152
	v_rcp_f32_e32 v153, v153
	v_rcp_f32_e32 v154, v154
	v_rcp_f32_e32 v155, v155
	v_rcp_f32_e32 v156, v156
	v_rcp_f32_e32 v157, v157
	v_rcp_f32_e32 v158, v158
	v_rcp_f32_e32 v159, v159
	v_mul_f32_e32 v152, v94, v152
	v_mul_f32_e32 v153, v95, v153
	v_mul_f32_e32 v154, v96, v154
	v_mul_f32_e32 v155, v97, v155
	v_mul_f32_e32 v156, v90, v156
	v_mul_f32_e32 v157, v91, v157
	v_mul_f32_e32 v158, v92, v158
	v_mul_f32_e32 v159, v93, v159
	v_cvt_pk_bf16_f32 v132, v152, v153
	v_cvt_pk_bf16_f32 v133, v154, v155
	v_cvt_pk_bf16_f32 v134, v156, v157
	v_cvt_pk_bf16_f32 v135, v158, v159
	s_add_u32 s46, s46, 0x8000
	s_addc_u32 s47, s47, 0
	global_store_dwordx4 v130, v[132:135], s[46:47] nt
	v_mul_f32_e32 v160, 0xbfb8aa3b, v86
	v_mul_f32_e32 v161, 0xbfb8aa3b, v87
	v_mul_f32_e32 v162, 0xbfb8aa3b, v88
	v_mul_f32_e32 v163, 0xbfb8aa3b, v89
	v_mul_f32_e32 v164, 0xbfb8aa3b, v82
	v_mul_f32_e32 v165, 0xbfb8aa3b, v83
	v_mul_f32_e32 v166, 0xbfb8aa3b, v84
	v_mul_f32_e32 v167, 0xbfb8aa3b, v85
	v_exp_f32_e32 v160, v160
	v_exp_f32_e32 v161, v161
	v_exp_f32_e32 v162, v162
	v_exp_f32_e32 v163, v163
	v_exp_f32_e32 v164, v164
	v_exp_f32_e32 v165, v165
	v_exp_f32_e32 v166, v166
	v_exp_f32_e32 v167, v167
	v_add_f32_e32 v160, 1.0, v160
	v_add_f32_e32 v161, 1.0, v161
	v_add_f32_e32 v162, 1.0, v162
	v_add_f32_e32 v163, 1.0, v163
	v_add_f32_e32 v164, 1.0, v164
	v_add_f32_e32 v165, 1.0, v165
	v_add_f32_e32 v166, 1.0, v166
	v_add_f32_e32 v167, 1.0, v167
	v_rcp_f32_e32 v160, v160
	v_rcp_f32_e32 v161, v161
	v_rcp_f32_e32 v162, v162
	v_rcp_f32_e32 v163, v163
	v_rcp_f32_e32 v164, v164
	v_rcp_f32_e32 v165, v165
	v_rcp_f32_e32 v166, v166
	v_rcp_f32_e32 v167, v167
	v_mul_f32_e32 v160, v86, v160
	v_mul_f32_e32 v161, v87, v161
	v_mul_f32_e32 v162, v88, v162
	v_mul_f32_e32 v163, v89, v163
	v_mul_f32_e32 v164, v82, v164
	v_mul_f32_e32 v165, v83, v165
	v_mul_f32_e32 v166, v84, v166
	v_mul_f32_e32 v167, v85, v167
	v_cvt_pk_bf16_f32 v168, v160, v161
	v_cvt_pk_bf16_f32 v169, v162, v163
	v_cvt_pk_bf16_f32 v170, v164, v165
	v_cvt_pk_bf16_f32 v171, v166, v167
	global_store_dwordx4 v130, v[168:171], s[46:47] offset:256 nt
	v_mul_f32_e32 v152, 0xbfb8aa3b, v78
	v_mul_f32_e32 v153, 0xbfb8aa3b, v79
	v_mul_f32_e32 v154, 0xbfb8aa3b, v80
	v_mul_f32_e32 v155, 0xbfb8aa3b, v81
	v_mul_f32_e32 v156, 0xbfb8aa3b, v74
	v_mul_f32_e32 v157, 0xbfb8aa3b, v75
	v_mul_f32_e32 v158, 0xbfb8aa3b, v76
	v_mul_f32_e32 v159, 0xbfb8aa3b, v77
	v_exp_f32_e32 v152, v152
	v_exp_f32_e32 v153, v153
	v_exp_f32_e32 v154, v154
	v_exp_f32_e32 v155, v155
	v_exp_f32_e32 v156, v156
	v_exp_f32_e32 v157, v157
	v_exp_f32_e32 v158, v158
	v_exp_f32_e32 v159, v159
	v_add_f32_e32 v152, 1.0, v152
	v_add_f32_e32 v153, 1.0, v153
	v_add_f32_e32 v154, 1.0, v154
	v_add_f32_e32 v155, 1.0, v155
	v_add_f32_e32 v156, 1.0, v156
	v_add_f32_e32 v157, 1.0, v157
	v_add_f32_e32 v158, 1.0, v158
	v_add_f32_e32 v159, 1.0, v159
	v_rcp_f32_e32 v152, v152
	v_rcp_f32_e32 v153, v153
	v_rcp_f32_e32 v154, v154
	v_rcp_f32_e32 v155, v155
	v_rcp_f32_e32 v156, v156
	v_rcp_f32_e32 v157, v157
	v_rcp_f32_e32 v158, v158
	v_rcp_f32_e32 v159, v159
	v_mul_f32_e32 v152, v78, v152
	v_mul_f32_e32 v153, v79, v153
	v_mul_f32_e32 v154, v80, v154
	v_mul_f32_e32 v155, v81, v155
	v_mul_f32_e32 v156, v74, v156
	v_mul_f32_e32 v157, v75, v157
	v_mul_f32_e32 v158, v76, v158
	v_mul_f32_e32 v159, v77, v159
	v_cvt_pk_bf16_f32 v132, v152, v153
	v_cvt_pk_bf16_f32 v133, v154, v155
	v_cvt_pk_bf16_f32 v134, v156, v157
	v_cvt_pk_bf16_f32 v135, v158, v159
	s_add_u32 s46, s46, 0x8000
	s_addc_u32 s47, s47, 0
	global_store_dwordx4 v130, v[132:135], s[46:47] nt
	v_mul_f32_e32 v160, 0xbfb8aa3b, v70
	v_mul_f32_e32 v161, 0xbfb8aa3b, v71
	v_mul_f32_e32 v162, 0xbfb8aa3b, v72
	v_mul_f32_e32 v163, 0xbfb8aa3b, v73
	v_mul_f32_e32 v164, 0xbfb8aa3b, v66
	v_mul_f32_e32 v165, 0xbfb8aa3b, v67
	v_mul_f32_e32 v166, 0xbfb8aa3b, v68
	v_mul_f32_e32 v167, 0xbfb8aa3b, v69
	v_exp_f32_e32 v160, v160
	v_exp_f32_e32 v161, v161
	v_exp_f32_e32 v162, v162
	v_exp_f32_e32 v163, v163
	v_exp_f32_e32 v164, v164
	v_exp_f32_e32 v165, v165
	v_exp_f32_e32 v166, v166
	v_exp_f32_e32 v167, v167
	v_add_f32_e32 v160, 1.0, v160
	v_add_f32_e32 v161, 1.0, v161
	v_add_f32_e32 v162, 1.0, v162
	v_add_f32_e32 v163, 1.0, v163
	v_add_f32_e32 v164, 1.0, v164
	v_add_f32_e32 v165, 1.0, v165
	v_add_f32_e32 v166, 1.0, v166
	v_add_f32_e32 v167, 1.0, v167
	v_rcp_f32_e32 v160, v160
	v_rcp_f32_e32 v161, v161
	v_rcp_f32_e32 v162, v162
	v_rcp_f32_e32 v163, v163
	v_rcp_f32_e32 v164, v164
	v_rcp_f32_e32 v165, v165
	v_rcp_f32_e32 v166, v166
	v_rcp_f32_e32 v167, v167
	v_mul_f32_e32 v160, v70, v160
	v_mul_f32_e32 v161, v71, v161
	v_mul_f32_e32 v162, v72, v162
	v_mul_f32_e32 v163, v73, v163
	v_mul_f32_e32 v164, v66, v164
	v_mul_f32_e32 v165, v67, v165
	v_mul_f32_e32 v166, v68, v166
	v_mul_f32_e32 v167, v69, v167
	v_cvt_pk_bf16_f32 v168, v160, v161
	v_cvt_pk_bf16_f32 v169, v162, v163
	v_cvt_pk_bf16_f32 v170, v164, v165
	v_cvt_pk_bf16_f32 v171, v166, v167
	global_store_dwordx4 v130, v[168:171], s[46:47] offset:256 nt
	v_mul_f32_e32 v152, 0xbfb8aa3b, v62
	v_mul_f32_e32 v153, 0xbfb8aa3b, v63
	v_mul_f32_e32 v154, 0xbfb8aa3b, v64
	v_mul_f32_e32 v155, 0xbfb8aa3b, v65
	v_mul_f32_e32 v156, 0xbfb8aa3b, v58
	v_mul_f32_e32 v157, 0xbfb8aa3b, v59
	v_mul_f32_e32 v158, 0xbfb8aa3b, v60
	v_mul_f32_e32 v159, 0xbfb8aa3b, v61
	v_exp_f32_e32 v152, v152
	v_exp_f32_e32 v153, v153
	v_exp_f32_e32 v154, v154
	v_exp_f32_e32 v155, v155
	v_exp_f32_e32 v156, v156
	v_exp_f32_e32 v157, v157
	v_exp_f32_e32 v158, v158
	v_exp_f32_e32 v159, v159
	v_add_f32_e32 v152, 1.0, v152
	v_add_f32_e32 v153, 1.0, v153
	v_add_f32_e32 v154, 1.0, v154
	v_add_f32_e32 v155, 1.0, v155
	v_add_f32_e32 v156, 1.0, v156
	v_add_f32_e32 v157, 1.0, v157
	v_add_f32_e32 v158, 1.0, v158
	v_add_f32_e32 v159, 1.0, v159
	v_rcp_f32_e32 v152, v152
	v_rcp_f32_e32 v153, v153
	v_rcp_f32_e32 v154, v154
	v_rcp_f32_e32 v155, v155
	v_rcp_f32_e32 v156, v156
	v_rcp_f32_e32 v157, v157
	v_rcp_f32_e32 v158, v158
	v_rcp_f32_e32 v159, v159
	v_mul_f32_e32 v152, v62, v152
	v_mul_f32_e32 v153, v63, v153
	v_mul_f32_e32 v154, v64, v154
	v_mul_f32_e32 v155, v65, v155
	v_mul_f32_e32 v156, v58, v156
	v_mul_f32_e32 v157, v59, v157
	v_mul_f32_e32 v158, v60, v158
	v_mul_f32_e32 v159, v61, v159
	v_cvt_pk_bf16_f32 v132, v152, v153
	v_cvt_pk_bf16_f32 v133, v154, v155
	v_cvt_pk_bf16_f32 v134, v156, v157
	v_cvt_pk_bf16_f32 v135, v158, v159
	s_add_u32 s46, s46, 0x28000
	s_addc_u32 s47, s47, 0
	global_store_dwordx4 v130, v[132:135], s[46:47] nt
	v_mul_f32_e32 v160, 0xbfb8aa3b, v54
	v_mul_f32_e32 v161, 0xbfb8aa3b, v55
	v_mul_f32_e32 v162, 0xbfb8aa3b, v56
	v_mul_f32_e32 v163, 0xbfb8aa3b, v57
	v_mul_f32_e32 v164, 0xbfb8aa3b, v50
	v_mul_f32_e32 v165, 0xbfb8aa3b, v51
	v_mul_f32_e32 v166, 0xbfb8aa3b, v52
	v_mul_f32_e32 v167, 0xbfb8aa3b, v53
	v_exp_f32_e32 v160, v160
	v_exp_f32_e32 v161, v161
	v_exp_f32_e32 v162, v162
	v_exp_f32_e32 v163, v163
	v_exp_f32_e32 v164, v164
	v_exp_f32_e32 v165, v165
	v_exp_f32_e32 v166, v166
	v_exp_f32_e32 v167, v167
	v_add_f32_e32 v160, 1.0, v160
	v_add_f32_e32 v161, 1.0, v161
	v_add_f32_e32 v162, 1.0, v162
	v_add_f32_e32 v163, 1.0, v163
	v_add_f32_e32 v164, 1.0, v164
	v_add_f32_e32 v165, 1.0, v165
	v_add_f32_e32 v166, 1.0, v166
	v_add_f32_e32 v167, 1.0, v167
	v_rcp_f32_e32 v160, v160
	v_rcp_f32_e32 v161, v161
	v_rcp_f32_e32 v162, v162
	v_rcp_f32_e32 v163, v163
	v_rcp_f32_e32 v164, v164
	v_rcp_f32_e32 v165, v165
	v_rcp_f32_e32 v166, v166
	v_rcp_f32_e32 v167, v167
	v_mul_f32_e32 v160, v54, v160
	v_mul_f32_e32 v161, v55, v161
	v_mul_f32_e32 v162, v56, v162
	v_mul_f32_e32 v163, v57, v163
	v_mul_f32_e32 v164, v50, v164
	v_mul_f32_e32 v165, v51, v165
	v_mul_f32_e32 v166, v52, v166
	v_mul_f32_e32 v167, v53, v167
	v_cvt_pk_bf16_f32 v168, v160, v161
	v_cvt_pk_bf16_f32 v169, v162, v163
	v_cvt_pk_bf16_f32 v170, v164, v165
	v_cvt_pk_bf16_f32 v171, v166, v167
	global_store_dwordx4 v130, v[168:171], s[46:47] offset:256 nt
	v_mul_f32_e32 v152, 0xbfb8aa3b, v46
	v_mul_f32_e32 v153, 0xbfb8aa3b, v47
	v_mul_f32_e32 v154, 0xbfb8aa3b, v48
	v_mul_f32_e32 v155, 0xbfb8aa3b, v49
	v_mul_f32_e32 v156, 0xbfb8aa3b, v42
	v_mul_f32_e32 v157, 0xbfb8aa3b, v43
	v_mul_f32_e32 v158, 0xbfb8aa3b, v44
	v_mul_f32_e32 v159, 0xbfb8aa3b, v45
	v_exp_f32_e32 v152, v152
	v_exp_f32_e32 v153, v153
	v_exp_f32_e32 v154, v154
	v_exp_f32_e32 v155, v155
	v_exp_f32_e32 v156, v156
	v_exp_f32_e32 v157, v157
	v_exp_f32_e32 v158, v158
	v_exp_f32_e32 v159, v159
	v_add_f32_e32 v152, 1.0, v152
	v_add_f32_e32 v153, 1.0, v153
	v_add_f32_e32 v154, 1.0, v154
	v_add_f32_e32 v155, 1.0, v155
	v_add_f32_e32 v156, 1.0, v156
	v_add_f32_e32 v157, 1.0, v157
	v_add_f32_e32 v158, 1.0, v158
	v_add_f32_e32 v159, 1.0, v159
	v_rcp_f32_e32 v152, v152
	v_rcp_f32_e32 v153, v153
	v_rcp_f32_e32 v154, v154
	v_rcp_f32_e32 v155, v155
	v_rcp_f32_e32 v156, v156
	v_rcp_f32_e32 v157, v157
	v_rcp_f32_e32 v158, v158
	v_rcp_f32_e32 v159, v159
	v_mul_f32_e32 v152, v46, v152
	v_mul_f32_e32 v153, v47, v153
	v_mul_f32_e32 v154, v48, v154
	v_mul_f32_e32 v155, v49, v155
	v_mul_f32_e32 v156, v42, v156
	v_mul_f32_e32 v157, v43, v157
	v_mul_f32_e32 v158, v44, v158
	v_mul_f32_e32 v159, v45, v159
	v_cvt_pk_bf16_f32 v132, v152, v153
	v_cvt_pk_bf16_f32 v133, v154, v155
	v_cvt_pk_bf16_f32 v134, v156, v157
	v_cvt_pk_bf16_f32 v135, v158, v159
	s_add_u32 s46, s46, 0x8000
	s_addc_u32 s47, s47, 0
	global_store_dwordx4 v130, v[132:135], s[46:47] nt
	v_mul_f32_e32 v160, 0xbfb8aa3b, v38
	v_mul_f32_e32 v161, 0xbfb8aa3b, v39
	v_mul_f32_e32 v162, 0xbfb8aa3b, v40
	v_mul_f32_e32 v163, 0xbfb8aa3b, v41
	v_mul_f32_e32 v164, 0xbfb8aa3b, v34
	v_mul_f32_e32 v165, 0xbfb8aa3b, v35
	v_mul_f32_e32 v166, 0xbfb8aa3b, v36
	v_mul_f32_e32 v167, 0xbfb8aa3b, v37
	v_exp_f32_e32 v160, v160
	v_exp_f32_e32 v161, v161
	v_exp_f32_e32 v162, v162
	v_exp_f32_e32 v163, v163
	v_exp_f32_e32 v164, v164
	v_exp_f32_e32 v165, v165
	v_exp_f32_e32 v166, v166
	v_exp_f32_e32 v167, v167
	v_add_f32_e32 v160, 1.0, v160
	v_add_f32_e32 v161, 1.0, v161
	v_add_f32_e32 v162, 1.0, v162
	v_add_f32_e32 v163, 1.0, v163
	v_add_f32_e32 v164, 1.0, v164
	v_add_f32_e32 v165, 1.0, v165
	v_add_f32_e32 v166, 1.0, v166
	v_add_f32_e32 v167, 1.0, v167
	v_rcp_f32_e32 v160, v160
	v_rcp_f32_e32 v161, v161
	v_rcp_f32_e32 v162, v162
	v_rcp_f32_e32 v163, v163
	v_rcp_f32_e32 v164, v164
	v_rcp_f32_e32 v165, v165
	v_rcp_f32_e32 v166, v166
	v_rcp_f32_e32 v167, v167
	v_mul_f32_e32 v160, v38, v160
	v_mul_f32_e32 v161, v39, v161
	v_mul_f32_e32 v162, v40, v162
	v_mul_f32_e32 v163, v41, v163
	v_mul_f32_e32 v164, v34, v164
	v_mul_f32_e32 v165, v35, v165
	v_mul_f32_e32 v166, v36, v166
	v_mul_f32_e32 v167, v37, v167
	v_cvt_pk_bf16_f32 v168, v160, v161
	v_cvt_pk_bf16_f32 v169, v162, v163
	v_cvt_pk_bf16_f32 v170, v164, v165
	v_cvt_pk_bf16_f32 v171, v166, v167
	global_store_dwordx4 v130, v[168:171], s[46:47] offset:256 nt
	v_mul_f32_e32 v152, 0xbfb8aa3b, v30
	v_mul_f32_e32 v153, 0xbfb8aa3b, v31
	v_mul_f32_e32 v154, 0xbfb8aa3b, v32
	v_mul_f32_e32 v155, 0xbfb8aa3b, v33
	v_mul_f32_e32 v156, 0xbfb8aa3b, v26
	v_mul_f32_e32 v157, 0xbfb8aa3b, v27
	v_mul_f32_e32 v158, 0xbfb8aa3b, v28
	v_mul_f32_e32 v159, 0xbfb8aa3b, v29
	v_exp_f32_e32 v152, v152
	v_exp_f32_e32 v153, v153
	v_exp_f32_e32 v154, v154
	v_exp_f32_e32 v155, v155
	v_exp_f32_e32 v156, v156
	v_exp_f32_e32 v157, v157
	v_exp_f32_e32 v158, v158
	v_exp_f32_e32 v159, v159
	v_add_f32_e32 v152, 1.0, v152
	v_add_f32_e32 v153, 1.0, v153
	v_add_f32_e32 v154, 1.0, v154
	v_add_f32_e32 v155, 1.0, v155
	v_add_f32_e32 v156, 1.0, v156
	v_add_f32_e32 v157, 1.0, v157
	v_add_f32_e32 v158, 1.0, v158
	v_add_f32_e32 v159, 1.0, v159
	v_rcp_f32_e32 v152, v152
	v_rcp_f32_e32 v153, v153
	v_rcp_f32_e32 v154, v154
	v_rcp_f32_e32 v155, v155
	v_rcp_f32_e32 v156, v156
	v_rcp_f32_e32 v157, v157
	v_rcp_f32_e32 v158, v158
	v_rcp_f32_e32 v159, v159
	v_mul_f32_e32 v152, v30, v152
	v_mul_f32_e32 v153, v31, v153
	v_mul_f32_e32 v154, v32, v154
	v_mul_f32_e32 v155, v33, v155
	v_mul_f32_e32 v156, v26, v156
	v_mul_f32_e32 v157, v27, v157
	v_mul_f32_e32 v158, v28, v158
	v_mul_f32_e32 v159, v29, v159
	v_cvt_pk_bf16_f32 v132, v152, v153
	v_cvt_pk_bf16_f32 v133, v154, v155
	v_cvt_pk_bf16_f32 v134, v156, v157
	v_cvt_pk_bf16_f32 v135, v158, v159
	s_add_u32 s46, s46, 0x8000
	s_addc_u32 s47, s47, 0
	global_store_dwordx4 v130, v[132:135], s[46:47] nt
	v_mul_f32_e32 v160, 0xbfb8aa3b, v22
	v_mul_f32_e32 v161, 0xbfb8aa3b, v23
	v_mul_f32_e32 v162, 0xbfb8aa3b, v24
	v_mul_f32_e32 v163, 0xbfb8aa3b, v25
	v_mul_f32_e32 v164, 0xbfb8aa3b, v18
	v_mul_f32_e32 v165, 0xbfb8aa3b, v19
	v_mul_f32_e32 v166, 0xbfb8aa3b, v20
	v_mul_f32_e32 v167, 0xbfb8aa3b, v21
	v_exp_f32_e32 v160, v160
	v_exp_f32_e32 v161, v161
	v_exp_f32_e32 v162, v162
	v_exp_f32_e32 v163, v163
	v_exp_f32_e32 v164, v164
	v_exp_f32_e32 v165, v165
	v_exp_f32_e32 v166, v166
	v_exp_f32_e32 v167, v167
	v_add_f32_e32 v160, 1.0, v160
	v_add_f32_e32 v161, 1.0, v161
	v_add_f32_e32 v162, 1.0, v162
	v_add_f32_e32 v163, 1.0, v163
	v_add_f32_e32 v164, 1.0, v164
	v_add_f32_e32 v165, 1.0, v165
	v_add_f32_e32 v166, 1.0, v166
	v_add_f32_e32 v167, 1.0, v167
	v_rcp_f32_e32 v160, v160
	v_rcp_f32_e32 v161, v161
	v_rcp_f32_e32 v162, v162
	v_rcp_f32_e32 v163, v163
	v_rcp_f32_e32 v164, v164
	v_rcp_f32_e32 v165, v165
	v_rcp_f32_e32 v166, v166
	v_rcp_f32_e32 v167, v167
	v_mul_f32_e32 v160, v22, v160
	v_mul_f32_e32 v161, v23, v161
	v_mul_f32_e32 v162, v24, v162
	v_mul_f32_e32 v163, v25, v163
	v_mul_f32_e32 v164, v18, v164
	v_mul_f32_e32 v165, v19, v165
	v_mul_f32_e32 v166, v20, v166
	v_mul_f32_e32 v167, v21, v167
	v_cvt_pk_bf16_f32 v168, v160, v161
	v_cvt_pk_bf16_f32 v169, v162, v163
	v_cvt_pk_bf16_f32 v170, v164, v165
	v_cvt_pk_bf16_f32 v171, v166, v167
	global_store_dwordx4 v130, v[168:171], s[46:47] offset:256 nt
	v_mul_f32_e32 v152, 0xbfb8aa3b, v14
	v_mul_f32_e32 v153, 0xbfb8aa3b, v15
	v_mul_f32_e32 v154, 0xbfb8aa3b, v16
	v_mul_f32_e32 v155, 0xbfb8aa3b, v17
	v_mul_f32_e32 v156, 0xbfb8aa3b, v10
	v_mul_f32_e32 v157, 0xbfb8aa3b, v11
	v_mul_f32_e32 v158, 0xbfb8aa3b, v12
	v_mul_f32_e32 v159, 0xbfb8aa3b, v13
	v_exp_f32_e32 v152, v152
	v_exp_f32_e32 v153, v153
	v_exp_f32_e32 v154, v154
	v_exp_f32_e32 v155, v155
	v_exp_f32_e32 v156, v156
	v_exp_f32_e32 v157, v157
	v_exp_f32_e32 v158, v158
	v_exp_f32_e32 v159, v159
	v_add_f32_e32 v152, 1.0, v152
	v_add_f32_e32 v153, 1.0, v153
	v_add_f32_e32 v154, 1.0, v154
	v_add_f32_e32 v155, 1.0, v155
	v_add_f32_e32 v156, 1.0, v156
	v_add_f32_e32 v157, 1.0, v157
	v_add_f32_e32 v158, 1.0, v158
	v_add_f32_e32 v159, 1.0, v159
	v_rcp_f32_e32 v152, v152
	v_rcp_f32_e32 v153, v153
	v_rcp_f32_e32 v154, v154
	v_rcp_f32_e32 v155, v155
	v_rcp_f32_e32 v156, v156
	v_rcp_f32_e32 v157, v157
	v_rcp_f32_e32 v158, v158
	v_rcp_f32_e32 v159, v159
	v_mul_f32_e32 v152, v14, v152
	v_mul_f32_e32 v153, v15, v153
	v_mul_f32_e32 v154, v16, v154
	v_mul_f32_e32 v155, v17, v155
	v_mul_f32_e32 v156, v10, v156
	v_mul_f32_e32 v157, v11, v157
	v_mul_f32_e32 v158, v12, v158
	v_mul_f32_e32 v159, v13, v159
	v_cvt_pk_bf16_f32 v132, v152, v153
	v_cvt_pk_bf16_f32 v133, v154, v155
	v_cvt_pk_bf16_f32 v134, v156, v157
	v_cvt_pk_bf16_f32 v135, v158, v159
	s_add_u32 s46, s46, 0x8000
	s_addc_u32 s47, s47, 0
	global_store_dwordx4 v130, v[132:135], s[46:47] nt
	v_mul_f32_e32 v160, 0xbfb8aa3b, v6
	v_mul_f32_e32 v161, 0xbfb8aa3b, v7
	v_mul_f32_e32 v162, 0xbfb8aa3b, v8
	v_mul_f32_e32 v163, 0xbfb8aa3b, v9
	v_mul_f32_e32 v164, 0xbfb8aa3b, v2
	v_mul_f32_e32 v165, 0xbfb8aa3b, v3
	v_mul_f32_e32 v166, 0xbfb8aa3b, v4
	v_mul_f32_e32 v167, 0xbfb8aa3b, v5
	v_exp_f32_e32 v160, v160
	v_exp_f32_e32 v161, v161
	v_exp_f32_e32 v162, v162
	v_exp_f32_e32 v163, v163
	v_exp_f32_e32 v164, v164
	v_exp_f32_e32 v165, v165
	v_exp_f32_e32 v166, v166
	v_exp_f32_e32 v167, v167
	v_add_f32_e32 v160, 1.0, v160
	v_add_f32_e32 v161, 1.0, v161
	v_add_f32_e32 v162, 1.0, v162
	v_add_f32_e32 v163, 1.0, v163
	v_add_f32_e32 v164, 1.0, v164
	v_add_f32_e32 v165, 1.0, v165
	v_add_f32_e32 v166, 1.0, v166
	v_add_f32_e32 v167, 1.0, v167
	v_rcp_f32_e32 v160, v160
	v_rcp_f32_e32 v161, v161
	v_rcp_f32_e32 v162, v162
	v_rcp_f32_e32 v163, v163
	v_rcp_f32_e32 v164, v164
	v_rcp_f32_e32 v165, v165
	v_rcp_f32_e32 v166, v166
	v_rcp_f32_e32 v167, v167
	v_mul_f32_e32 v160, v6, v160
	v_mul_f32_e32 v161, v7, v161
	v_mul_f32_e32 v162, v8, v162
	v_mul_f32_e32 v163, v9, v163
	v_mul_f32_e32 v164, v2, v164
	v_mul_f32_e32 v165, v3, v165
	v_mul_f32_e32 v166, v4, v166
	v_mul_f32_e32 v167, v5, v167
	v_cvt_pk_bf16_f32 v168, v160, v161
	v_cvt_pk_bf16_f32 v169, v162, v163
	v_cvt_pk_bf16_f32 v170, v164, v165
	v_cvt_pk_bf16_f32 v171, v166, v167
	global_store_dwordx4 v130, v[168:171], s[46:47] offset:256 nt
	s_branch .LBB0_1251
